# NSA sel/window loops: second half-tile K-fragment LDS reads issued before the first half PV MFMAs (5 of 6 steps), on top of bias-read hoist
# speedup vs baseline: 1.0009x; 1.0002x over previous
; template <int MODE>
; __device__ __forceinline__ void nsa_compute(int cur, int buf, int t, int hl, u64 mymask, const bf16x8 (&Qf)[2][2], f32x4 (&O)[4][2], float (&m)[2], float (&l)[2],
;                                             const float (&inv)[2], float* impw, char* lds) {
;     ...
;     for (int ks = 0; ks < 2; ++ks)
; #pragma unroll
;       for (int kk = 0; kk < 2; ++kk) kfr[ks][kk] = *(const bf16x8*)(kt + (32 * s2 + 16 * kk + fr) * 128 + (((ks * 4 + fq) ^ (fr & 7)) << 4));
;     __builtin_amdgcn_s_setprio(1);
; #pragma unroll
;     for (int ks = 0; ks < 2; ++ks)
; #pragma unroll
;       for (int kk = 0; kk < 2; ++kk)
; #pragma unroll
;         for (int r = 0; r < 2; ++r) S[kk][r] = mfma16(kfr[ks][kk], Qf[r][ks], S[kk][r]);
;     __builtin_amdgcn_s_setprio(0);
;     bf16x8 Pf[2];
;     float g1s[2] = {0.f, 0.f}, p3s[2] = {0.f, 0.f};
; #pragma unroll
;     for (int r = 0; r < 2; ++r) {
;       float sv[2][4];
; #pragma unroll
;       for (int kk = 0; kk < 2; ++kk)
; #pragma unroll
;         for (int e = 0; e < 4; ++e) {
;           const int off = 32 * s2 + 16 * kk + e;
;           int idx;
;           if (MODE <= 1) { idx = base - 16 * off; idx = idx > 0 ? idx : 0; } else idx = base - off;
;     ...
;           for (int e = 0; e < 4; ++e) { pv[kk][e] = __builtin_amdgcn_exp2f(sv[kk][e] - me); ps += pv[kk][e]; }
;         l[r] += ps;
;       }
;       if (MODE != 0) {
;         const unsigned w0 = pk2(pv[0][0], pv[0][1]), w1 = pk2(pv[0][2], pv[0][3]), w2 = pk2(pv[1][0], pv[1][1]), w3 = pk2(pv[1][2], pv[1][3]);
;         u32x4 pw; pw.x = w0; pw.y = w1; pw.z = w2; pw.w = w3;
;         Pf[r] = __builtin_bit_cast(bf16x8, pw);
;       }
;     }
;     if (MODE != 0) {
;       bf16x8 vfr[4];
; #pragma unroll
;       for (int df = 0; df < 4; ++df) {
;         const bf16x4 va = *(const bf16x4*)(vt + (df * 16 + fr) * 68 + 32 * s2 + 4 * fq);
;         const bf16x4 vb = *(const bf16x4*)(vt + (df * 16 + fr) * 68 + 32 * s2 + 16 + 4 * fq);
;         bf16x8 vf; vf[0] = va[0]; vf[1] = va[1]; vf[2] = va[2]; vf[3] = va[3]; vf[4] = vb[0]; vf[5] = vb[1]; vf[6] = vb[2]; vf[7] = vb[3];
;         vfr[df] = vf;
;       }
;       __builtin_amdgcn_s_setprio(1);
; #pragma unroll
;       for (int df = 0; df < 4; ++df)
; #pragma unroll
;         for (int r = 0; r < 2; ++r) O[df][r] = mfma16(vfr[df], Pf[r], O[df][r]);
;       __builtin_amdgcn_s_setprio(0);
.LBB0_367:
	v_sub_f32_e32 v75, v81, v74
	v_exp_f32_e32 v75, v75
	v_sub_f32_e32 v80, v80, v74
	v_exp_f32_e32 v80, v80
	v_sub_f32_e32 v78, v78, v74
	v_exp_f32_e32 v78, v78
	v_sub_f32_e32 v81, v82, v74
	v_exp_f32_e32 v81, v81
	v_sub_f32_e32 v77, v77, v74
	v_add_f32_e32 v79, 0, v75
	v_exp_f32_e32 v77, v77
	v_sub_f32_e32 v76, v76, v74
	v_add_f32_e32 v79, v80, v79
	v_exp_f32_e32 v76, v76
	v_sub_f32_e32 v73, v73, v74
	v_add_f32_e32 v79, v78, v79
	v_exp_f32_e32 v73, v73
	v_sub_f32_e32 v72, v72, v74
	v_add_f32_e32 v79, v81, v79
	v_exp_f32_e32 v72, v72
	v_add_f32_e32 v79, v77, v79
	v_add_f32_e32 v79, v76, v79
	v_add_f32_e32 v79, v73, v79
	s_lshl_b32 s17, s46, 9
	v_add_f32_e32 v74, v72, v79
	v_cvt_pk_bf16_f32 v149, v73, v72
	v_mul_u32_u24_e32 v72, 0x44, v92
	s_add_i32 s43, s64, s17
	v_lshlrev_b32_e32 v72, 1, v72
	v_lshlrev_b32_e32 v73, 1, v93
	v_cvt_pk_bf16_f32 v146, v75, v80
	v_add3_u32 v80, s43, v72, v73
	v_add_u32_e32 v137, 0x4000, v80
	v_add_u32_e32 v138, 0x4800, v80
	v_add_f32_e32 v191, v191, v74
	v_cvt_pk_bf16_f32 v147, v78, v81
	v_cvt_pk_bf16_f32 v148, v77, v76
	ds_read2_b64 v[72:75], v137 offset1:4
	ds_read2_b64 v[76:79], v138 offset0:16 offset1:20
	v_add_u32_e32 v139, 0x5000, v80
	v_add_u32_e32 v140, 0x5800, v80
	ds_read2_b64 v[150:153], v139 offset0:32 offset1:36
	ds_read2_b64 v[154:157], v140 offset0:48 offset1:52
	v_cvt_pk_bf16_f32 v142, v85, v86
	v_cvt_pk_bf16_f32 v143, v87, v84
	v_cvt_pk_bf16_f32 v144, v89, v94
	v_cvt_pk_bf16_f32 v145, v95, v88
	v_add_u32_e32 v141, v91, v90
	v_add_u32_e32 v176, v100, v90
	ds_read_b128 v[206:209], v141 offset:4096
	ds_read_b128 v[236:239], v141 offset:6144
	ds_read_b128 v[240:243], v176 offset:4096
	ds_read_b128 v[244:247], v176 offset:6144
	s_setprio 1
	s_waitcnt lgkmcnt(7)
	v_mfma_f32_16x16x32_bf16 v[84:87], v[72:75], v[142:145], v[116:119]
	v_mfma_f32_16x16x32_bf16 v[96:99], v[72:75], v[146:149], v[104:107]
	s_waitcnt lgkmcnt(6)
	v_mfma_f32_16x16x32_bf16 v[80:83], v[76:79], v[142:145], v[124:127]
	v_mfma_f32_16x16x32_bf16 v[92:95], v[76:79], v[146:149], v[108:111]
	s_waitcnt lgkmcnt(5)
	v_mfma_f32_16x16x32_bf16 v[76:79], v[150:153], v[142:145], v[128:131]
	v_mfma_f32_16x16x32_bf16 v[108:111], v[150:153], v[146:149], v[112:115]
	s_waitcnt lgkmcnt(4)
	v_mfma_f32_16x16x32_bf16 v[72:75], v[154:157], v[142:145], v[132:135]
	v_mfma_f32_16x16x32_bf16 v[104:107], v[154:157], v[146:149], v[120:123]
	s_setprio 0
	v_add_u32_e32 v88, v91, v90
	v_add_u32_e32 v100, v100, v90
	v_add_u32_e32 v251, 0xa00, v136
	ds_read2_b32 v[168:169], v136 offset0:31 offset1:32
	ds_read2_b32 v[170:171], v136 offset0:29 offset1:30
	ds_read2_b32 v[172:173], v136 offset0:15 offset1:16
	ds_read2_b32 v[174:175], v136 offset0:13 offset1:14
	ds_read2_b32 v[198:199], v251 offset0:31 offset1:32
	ds_read2_b32 v[200:201], v251 offset0:29 offset1:30
	ds_read2_b32 v[202:203], v251 offset0:15 offset1:16
	ds_read2_b32 v[204:205], v251 offset0:13 offset1:14
	s_setprio 1
	s_waitcnt lgkmcnt(11)
	v_mfma_f32_16x16x32_bf16 v[100:103], v[206:209], v[0:3], 0
	v_mfma_f32_16x16x32_bf16 v[112:115], v[206:209], v[8:11], 0
	s_waitcnt lgkmcnt(10)
	v_mfma_f32_16x16x32_bf16 v[124:127], v[236:239], v[0:3], 0
	v_mfma_f32_16x16x32_bf16 v[116:119], v[236:239], v[8:11], 0
	s_waitcnt lgkmcnt(9)
	v_mfma_f32_16x16x32_bf16 v[128:131], v[240:243], v[4:7], v[100:103]
	v_mfma_f32_16x16x32_bf16 v[100:103], v[240:243], v[12:15], v[112:115]
	s_waitcnt lgkmcnt(8)
	v_mfma_f32_16x16x32_bf16 v[88:91], v[244:247], v[12:15], v[116:119]
	v_mfma_f32_16x16x32_bf16 v[124:127], v[244:247], v[4:7], v[124:127]
	s_setprio 0
	s_nop 0
	s_waitcnt lgkmcnt(7)
	s_nop 0
	v_fmamk_f32 v123, v128, 0x3e38aa3b, v169
	v_fmamk_f32 v118, v129, 0x3e38aa3b, v168
	s_waitcnt lgkmcnt(6)
	v_fmamk_f32 v122, v130, 0x3e38aa3b, v171
	v_fmamk_f32 v116, v131, 0x3e38aa3b, v170
	s_waitcnt lgkmcnt(5)
	v_fmamk_f32 v119, v124, 0x3e38aa3b, v173
	v_fmamk_f32 v114, v125, 0x3e38aa3b, v172
	s_waitcnt lgkmcnt(4)
	v_fmamk_f32 v113, v126, 0x3e38aa3b, v175
	v_fmamk_f32 v112, v127, 0x3e38aa3b, v174
	v_max3_f32 v115, v123, v118, v122
	v_max3_f32 v117, v116, v119, v114
	v_max_f32_e32 v120, v113, v112
	v_max3_f32 v115, v120, v115, v117
	v_add_f32_e32 v117, 0x41000000, v192
	v_cmp_gt_f32_e32 vcc, v115, v117
	s_cbranch_vccz .LBB0_369
	ds_bpermute_b32 v117, v233, v115
	v_max_f32_e32 v115, v115, v115
	v_mov_b32_e32 v121, v193
	s_waitcnt lgkmcnt(0)
	v_max_f32_e32 v117, v117, v117
	v_max_f32_e32 v115, v115, v117
	ds_bpermute_b32 v117, v234, v115
	s_waitcnt lgkmcnt(0)
	v_max3_f32 v120, v192, v115, v117
	v_sub_f32_e32 v115, v192, v120
	v_exp_f32_e32 v124, v115
	v_mov_b64_e32 v[192:193], v[120:121]
	v_mul_f32_e32 v190, v190, v124
	v_pk_mul_f32 v[86:87], v[86:87], v[124:125] op_sel_hi:[1,0]
	v_pk_mul_f32 v[84:85], v[84:85], v[124:125] op_sel_hi:[1,0]
	v_pk_mul_f32 v[82:83], v[82:83], v[124:125] op_sel_hi:[1,0]
	v_pk_mul_f32 v[80:81], v[80:81], v[124:125] op_sel_hi:[1,0]
	v_pk_mul_f32 v[78:79], v[78:79], v[124:125] op_sel_hi:[1,0]
	v_pk_mul_f32 v[76:77], v[76:77], v[124:125] op_sel_hi:[1,0]
	v_pk_mul_f32 v[74:75], v[74:75], v[124:125] op_sel_hi:[1,0]
	v_pk_mul_f32 v[72:73], v[72:73], v[124:125] op_sel_hi:[1,0]
	s_branch .LBB0_370

; template <int MODE>
; __device__ __forceinline__ void nsa_compute(int cur, int buf, int t, int hl, u64 mymask, const bf16x8 (&Qf)[2][2], f32x4 (&O)[4][2], float (&m)[2], float (&l)[2],
;                                             const float (&inv)[2], float* impw, char* lds) {
;     ...
;     for (int ks = 0; ks < 2; ++ks)
; #pragma unroll
;       for (int kk = 0; kk < 2; ++kk) kfr[ks][kk] = *(const bf16x8*)(kt + (32 * s2 + 16 * kk + fr) * 128 + (((ks * 4 + fq) ^ (fr & 7)) << 4));
;     __builtin_amdgcn_s_setprio(1);
; #pragma unroll
;     for (int ks = 0; ks < 2; ++ks)
; #pragma unroll
;       for (int kk = 0; kk < 2; ++kk)
; #pragma unroll
;         for (int r = 0; r < 2; ++r) S[kk][r] = mfma16(kfr[ks][kk], Qf[r][ks], S[kk][r]);
;     __builtin_amdgcn_s_setprio(0);
;     bf16x8 Pf[2];
;     float g1s[2] = {0.f, 0.f}, p3s[2] = {0.f, 0.f};
; #pragma unroll
;     for (int r = 0; r < 2; ++r) {
;       float sv[2][4];
; #pragma unroll
;       for (int kk = 0; kk < 2; ++kk)
; #pragma unroll
;         for (int e = 0; e < 4; ++e) {
;           const int off = 32 * s2 + 16 * kk + e;
;           int idx;
;           if (MODE <= 1) { idx = base - 16 * off; idx = idx > 0 ? idx : 0; } else idx = base - off;
;     ...
;           for (int e = 0; e < 4; ++e) { pv[kk][e] = __builtin_amdgcn_exp2f(sv[kk][e] - me); ps += pv[kk][e]; }
;         l[r] += ps;
;       }
;       if (MODE != 0) {
;         const unsigned w0 = pk2(pv[0][0], pv[0][1]), w1 = pk2(pv[0][2], pv[0][3]), w2 = pk2(pv[1][0], pv[1][1]), w3 = pk2(pv[1][2], pv[1][3]);
;         u32x4 pw; pw.x = w0; pw.y = w1; pw.z = w2; pw.w = w3;
;         Pf[r] = __builtin_bit_cast(bf16x8, pw);
;       }
;     }
;     if (MODE != 0) {
;       bf16x8 vfr[4];
; #pragma unroll
;       for (int df = 0; df < 4; ++df) {
;         const bf16x4 va = *(const bf16x4*)(vt + (df * 16 + fr) * 68 + 32 * s2 + 4 * fq);
;         const bf16x4 vb = *(const bf16x4*)(vt + (df * 16 + fr) * 68 + 32 * s2 + 16 + 4 * fq);
;         bf16x8 vf; vf[0] = va[0]; vf[1] = va[1]; vf[2] = va[2]; vf[3] = va[3]; vf[4] = vb[0]; vf[5] = vb[1]; vf[6] = vb[2]; vf[7] = vb[3];
;         vfr[df] = vf;
;       }
;       __builtin_amdgcn_s_setprio(1);
; #pragma unroll
;       for (int df = 0; df < 4; ++df)
; #pragma unroll
;         for (int r = 0; r < 2; ++r) O[df][r] = mfma16(vfr[df], Pf[r], O[df][r]);
;       __builtin_amdgcn_s_setprio(0);
.LBB0_385:
	v_sub_f32_e32 v119, v135, v118
	v_exp_f32_e32 v119, v119
	v_sub_f32_e32 v134, v134, v118
	v_exp_f32_e32 v134, v134
	v_sub_f32_e32 v145, v145, v118
	v_exp_f32_e32 v145, v145
	v_sub_f32_e32 v144, v144, v118
	v_exp_f32_e32 v144, v144
	v_sub_f32_e32 v133, v133, v118
	v_add_f32_e32 v135, 0, v119
	v_exp_f32_e32 v133, v133
	v_sub_f32_e32 v132, v132, v118
	v_add_f32_e32 v135, v134, v135
	v_exp_f32_e32 v132, v132
	v_sub_f32_e32 v117, v117, v118
	v_add_f32_e32 v135, v145, v135
	v_exp_f32_e32 v117, v117
	v_sub_f32_e32 v116, v116, v118
	v_add_f32_e32 v135, v144, v135
	v_exp_f32_e32 v116, v116
	v_add_f32_e32 v135, v133, v135
	v_add_f32_e32 v135, v132, v135
	v_add_f32_e32 v135, v117, v135
	s_lshl_b32 s16, s46, 9
	v_add_f32_e32 v118, v116, v135
	v_cvt_pk_bf16_f32 v167, v117, v116
	v_mul_u32_u24_e32 v116, 0x44, v149
	s_add_i32 s72, s71, s16
	v_lshlrev_b32_e32 v116, 1, v116
	v_lshlrev_b32_e32 v117, 1, v150
	v_add3_u32 v116, s72, v116, v117
	v_cvt_pk_bf16_f32 v161, v153, v155
	v_cvt_pk_bf16_f32 v162, v156, v157
	v_add_u32_e32 v155, 0x4000, v116
	v_add_u32_e32 v156, 0x4800, v116
	v_cvt_pk_bf16_f32 v160, v151, v152
	v_cvt_pk_bf16_f32 v163, v158, v159
	v_cvt_pk_bf16_f32 v164, v119, v134
	v_cvt_pk_bf16_f32 v166, v133, v132
	ds_read2_b64 v[132:135], v155 offset1:4
	ds_read2_b64 v[150:153], v156 offset0:16 offset1:20
	v_add_u32_e32 v157, 0x5000, v116
	v_add_u32_e32 v158, 0x5800, v116
	ds_read2_b64 v[168:171], v157 offset0:32 offset1:36
	ds_read2_b64 v[172:175], v158 offset0:48 offset1:52
	v_add_f32_e32 v197, v197, v118
	v_cvt_pk_bf16_f32 v165, v145, v144
	v_add_u32_e32 v159, v147, v146
	v_add_u32_e32 v176, v148, v146
	ds_read_b128 v[198:201], v159 offset:4096
	ds_read_b128 v[242:245], v159 offset:6144
	ds_read_b128 v[246:249], v176 offset:4096
	s_setprio 1
	s_waitcnt lgkmcnt(6)
	v_mfma_f32_16x16x32_bf16 v[116:119], v[132:135], v[160:163], v[112:115]
	v_mfma_f32_16x16x32_bf16 v[132:135], v[132:135], v[164:167], v[124:127]
	s_waitcnt lgkmcnt(5)
	v_mfma_f32_16x16x32_bf16 v[112:115], v[150:153], v[160:163], v[104:107]
	v_mfma_f32_16x16x32_bf16 v[128:131], v[150:153], v[164:167], v[128:131]
	s_waitcnt lgkmcnt(4)
	v_mfma_f32_16x16x32_bf16 v[108:111], v[168:171], v[160:163], v[108:111]
	v_mfma_f32_16x16x32_bf16 v[124:127], v[168:171], v[164:167], v[136:139]
	s_waitcnt lgkmcnt(3)
	v_mfma_f32_16x16x32_bf16 v[104:107], v[172:175], v[160:163], v[120:123]
	v_mfma_f32_16x16x32_bf16 v[120:123], v[172:175], v[164:167], v[140:143]
	s_setprio 0
	s_nop 1
	v_add_u32_e32 v140, v147, v146
	v_add_u32_e32 v148, v148, v146
	ds_read_b128 v[148:151], v148 offset:6144
	v_add_u32_e32 v251, 0xa00, v154
	ds_read2_b32 v[202:203], v154 offset0:31 offset1:32
	ds_read2_b32 v[204:205], v154 offset0:29 offset1:30
	ds_read2_b32 v[206:207], v154 offset0:15 offset1:16
	ds_read2_b32 v[208:209], v154 offset0:13 offset1:14
	ds_read2_b32 v[210:211], v251 offset0:31 offset1:32
	ds_read2_b32 v[236:237], v251 offset0:29 offset1:30
	ds_read2_b32 v[238:239], v251 offset0:15 offset1:16
	ds_read2_b32 v[240:241], v251 offset0:13 offset1:14
	s_setprio 1
	s_waitcnt lgkmcnt(11)
	v_mfma_f32_16x16x32_bf16 v[160:163], v[198:201], v[0:3], 0
	v_mfma_f32_16x16x32_bf16 v[136:139], v[198:201], v[8:11], 0
	s_waitcnt lgkmcnt(10)
	v_mfma_f32_16x16x32_bf16 v[168:171], v[242:245], v[8:11], 0
	v_mfma_f32_16x16x32_bf16 v[164:167], v[242:245], v[0:3], 0
	s_waitcnt lgkmcnt(9)
	v_mfma_f32_16x16x32_bf16 v[160:163], v[246:249], v[4:7], v[160:163]
	v_mfma_f32_16x16x32_bf16 v[140:143], v[246:249], v[12:15], v[136:139]
	s_waitcnt lgkmcnt(8)
	v_mfma_f32_16x16x32_bf16 v[136:139], v[148:151], v[12:15], v[168:171]
	v_mfma_f32_16x16x32_bf16 v[164:167], v[148:151], v[4:7], v[164:167]
	s_setprio 0
	s_waitcnt lgkmcnt(7)
	s_nop 1
	v_fmamk_f32 v160, v160, 0x3e38aa3b, v203
	v_fmamk_f32 v150, v161, 0x3e38aa3b, v202
	s_waitcnt lgkmcnt(6)
	v_fmamk_f32 v159, v162, 0x3e38aa3b, v205
	v_fmamk_f32 v148, v163, 0x3e38aa3b, v204
	s_waitcnt lgkmcnt(5)
	v_fmamk_f32 v151, v164, 0x3e38aa3b, v207
	v_fmamk_f32 v146, v165, 0x3e38aa3b, v206
	s_waitcnt lgkmcnt(4)
	v_fmamk_f32 v145, v166, 0x3e38aa3b, v209
	v_fmamk_f32 v144, v167, 0x3e38aa3b, v208
	v_max3_f32 v147, v160, v150, v159
	v_max3_f32 v149, v148, v151, v146
	v_max_f32_e32 v152, v145, v144
	v_max3_f32 v147, v152, v147, v149
	v_add_f32_e32 v149, 0x41000000, v192
	v_cmp_gt_f32_e32 vcc, v147, v149
	s_cbranch_vccz .LBB0_387
	ds_bpermute_b32 v149, v233, v147
	v_max_f32_e32 v147, v147, v147
	v_mov_b32_e32 v153, v193
	s_waitcnt lgkmcnt(0)
	v_max_f32_e32 v149, v149, v149
	v_max_f32_e32 v147, v147, v149
	ds_bpermute_b32 v149, v234, v147
	s_waitcnt lgkmcnt(0)
	v_max3_f32 v152, v192, v147, v149
	v_sub_f32_e32 v147, v192, v152
	v_exp_f32_e32 v162, v147
	v_mov_b64_e32 v[192:193], v[152:153]
	v_mul_f32_e32 v196, v196, v162
	v_pk_mul_f32 v[118:119], v[118:119], v[162:163] op_sel_hi:[1,0]
	v_pk_mul_f32 v[116:117], v[116:117], v[162:163] op_sel_hi:[1,0]
	v_pk_mul_f32 v[114:115], v[114:115], v[162:163] op_sel_hi:[1,0]
	v_pk_mul_f32 v[112:113], v[112:113], v[162:163] op_sel_hi:[1,0]
	v_pk_mul_f32 v[110:111], v[110:111], v[162:163] op_sel_hi:[1,0]
	v_pk_mul_f32 v[108:109], v[108:109], v[162:163] op_sel_hi:[1,0]
	v_pk_mul_f32 v[106:107], v[106:107], v[162:163] op_sel_hi:[1,0]
	v_pk_mul_f32 v[104:105], v[104:105], v[162:163] op_sel_hi:[1,0]
	s_branch .LBB0_388

; template <int MODE>
; __device__ __forceinline__ void nsa_compute(int cur, int buf, int t, int hl, u64 mymask, const bf16x8 (&Qf)[2][2], f32x4 (&O)[4][2], float (&m)[2], float (&l)[2],
;                                             const float (&inv)[2], float* impw, char* lds) {
;     ...
;     for (int ks = 0; ks < 2; ++ks)
; #pragma unroll
;       for (int kk = 0; kk < 2; ++kk) kfr[ks][kk] = *(const bf16x8*)(kt + (32 * s2 + 16 * kk + fr) * 128 + (((ks * 4 + fq) ^ (fr & 7)) << 4));
;     __builtin_amdgcn_s_setprio(1);
; #pragma unroll
;     for (int ks = 0; ks < 2; ++ks)
; #pragma unroll
;       for (int kk = 0; kk < 2; ++kk)
; #pragma unroll
;         for (int r = 0; r < 2; ++r) S[kk][r] = mfma16(kfr[ks][kk], Qf[r][ks], S[kk][r]);
;     __builtin_amdgcn_s_setprio(0);
;     bf16x8 Pf[2];
;     float g1s[2] = {0.f, 0.f}, p3s[2] = {0.f, 0.f};
; #pragma unroll
;     for (int r = 0; r < 2; ++r) {
;       float sv[2][4];
; #pragma unroll
;       for (int kk = 0; kk < 2; ++kk)
; #pragma unroll
;         for (int e = 0; e < 4; ++e) {
;           const int off = 32 * s2 + 16 * kk + e;
;           int idx;
;           if (MODE <= 1) { idx = base - 16 * off; idx = idx > 0 ? idx : 0; } else idx = base - off;
;     ...
;           for (int e = 0; e < 4; ++e) { pv[kk][e] = __builtin_amdgcn_exp2f(sv[kk][e] - me); ps += pv[kk][e]; }
;         l[r] += ps;
;       }
;       if (MODE != 0) {
;         const unsigned w0 = pk2(pv[0][0], pv[0][1]), w1 = pk2(pv[0][2], pv[0][3]), w2 = pk2(pv[1][0], pv[1][1]), w3 = pk2(pv[1][2], pv[1][3]);
;         u32x4 pw; pw.x = w0; pw.y = w1; pw.z = w2; pw.w = w3;
;         Pf[r] = __builtin_bit_cast(bf16x8, pw);
;       }
;     }
;     if (MODE != 0) {
;       bf16x8 vfr[4];
; #pragma unroll
;       for (int df = 0; df < 4; ++df) {
;         const bf16x4 va = *(const bf16x4*)(vt + (df * 16 + fr) * 68 + 32 * s2 + 4 * fq);
;         const bf16x4 vb = *(const bf16x4*)(vt + (df * 16 + fr) * 68 + 32 * s2 + 16 + 4 * fq);
;         bf16x8 vf; vf[0] = va[0]; vf[1] = va[1]; vf[2] = va[2]; vf[3] = va[3]; vf[4] = vb[0]; vf[5] = vb[1]; vf[6] = vb[2]; vf[7] = vb[3];
;         vfr[df] = vf;
;       }
;       __builtin_amdgcn_s_setprio(1);
; #pragma unroll
;       for (int df = 0; df < 4; ++df)
; #pragma unroll
;         for (int r = 0; r < 2; ++r) O[df][r] = mfma16(vfr[df], Pf[r], O[df][r]);
;       __builtin_amdgcn_s_setprio(0);
.LBB0_442:
	v_cndmask_b32_e64 v74, v74, v228, s[36:37]
	v_sub_f32_e32 v75, v81, v74
	v_exp_f32_e32 v75, v75
	v_sub_f32_e32 v80, v80, v74
	v_exp_f32_e32 v80, v80
	v_sub_f32_e32 v78, v78, v74
	v_exp_f32_e32 v78, v78
	v_sub_f32_e32 v81, v82, v74
	v_exp_f32_e32 v81, v81
	v_sub_f32_e32 v77, v77, v74
	v_add_f32_e32 v79, 0, v75
	v_exp_f32_e32 v77, v77
	v_sub_f32_e32 v76, v76, v74
	v_add_f32_e32 v79, v80, v79
	v_exp_f32_e32 v76, v76
	v_sub_f32_e32 v73, v73, v74
	v_add_f32_e32 v79, v78, v79
	v_exp_f32_e32 v73, v73
	v_sub_f32_e32 v72, v72, v74
	v_add_f32_e32 v79, v81, v79
	v_exp_f32_e32 v72, v72
	v_add_f32_e32 v79, v77, v79
	v_add_f32_e32 v79, v76, v79
	v_add_f32_e32 v79, v73, v79
	s_lshl_b32 s17, s74, 9
	v_add_f32_e32 v74, v72, v79
	v_cvt_pk_bf16_f32 v101, v73, v72
	v_mul_u32_u24_e32 v72, 0x44, v94
	s_add_i32 s71, s63, s17
	v_lshlrev_b32_e32 v72, 1, v72
	v_lshlrev_b32_e32 v73, 1, v95
	v_add3_u32 v72, s71, v72, v73
	v_add_u32_e32 v94, 0x4000, v72
	v_cvt_pk_bf16_f32 v87, v87, v88
	v_cvt_pk_bf16_f32 v88, v89, v96
	v_cvt_pk_bf16_f32 v89, v97, v84
	v_cvt_pk_bf16_f32 v99, v78, v81
	v_cvt_pk_bf16_f32 v100, v77, v76
	ds_read2_b64 v[76:79], v94 offset1:4
	v_add_u32_e32 v95, 0x4800, v72
	v_add_u32_e32 v96, 0x5000, v72
	v_add_u32_e32 v97, 0x5800, v72
	ds_read2_b64 v[102:105], v95 offset0:16 offset1:20
	ds_read2_b64 v[106:109], v96 offset0:32 offset1:36
	ds_read2_b64 v[110:113], v97 offset0:48 offset1:52
	v_cvt_pk_bf16_f32 v86, v85, v86
	v_add_f32_e32 v191, v191, v74
	v_cvt_pk_bf16_f32 v98, v75, v80
	v_add_u32_e32 v114, v92, v91
	v_add_u32_e32 v115, v93, v91
	ds_read_b128 v[116:119], v114 offset:4096
	ds_read_b128 v[168:171], v114 offset:6144
	ds_read_b128 v[172:175], v115 offset:4096
	ds_read_b128 v[192:195], v115 offset:6144
	s_setprio 1
	s_waitcnt lgkmcnt(7)
	v_mfma_f32_16x16x32_bf16 v[72:75], v[76:79], v[86:89], v[16:19]
	v_mfma_f32_16x16x32_bf16 v[80:83], v[76:79], v[98:101], v[20:23]
	s_waitcnt lgkmcnt(6)
	v_mfma_f32_16x16x32_bf16 v[24:27], v[102:105], v[86:89], v[24:27]
	v_mfma_f32_16x16x32_bf16 v[76:79], v[102:105], v[98:101], v[28:31]
	s_waitcnt lgkmcnt(5)
	v_mfma_f32_16x16x32_bf16 v[20:23], v[106:109], v[86:89], v[32:35]
	v_mfma_f32_16x16x32_bf16 v[32:35], v[106:109], v[98:101], v[36:39]
	s_waitcnt lgkmcnt(4)
	v_mfma_f32_16x16x32_bf16 v[16:19], v[110:113], v[86:89], v[40:43]
	v_mfma_f32_16x16x32_bf16 v[28:31], v[110:113], v[98:101], v[44:47]
	s_setprio 0
	s_nop 0
	v_add_u32_e32 v40, v92, v91
	v_add_u32_e32 v84, v93, v91
	v_add_u32_e32 v251, 0x8400, v90
	v_add_u32_e32 v250, 0xc500, v90
	ds_read2_b32 v[138:139], v251 offset0:31 offset1:32
	ds_read2_b32 v[140:141], v251 offset0:29 offset1:30
	ds_read2_b32 v[142:143], v251 offset0:15 offset1:16
	ds_read2_b32 v[148:149], v251 offset0:13 offset1:14
	ds_read2_b32 v[150:151], v250 offset0:31 offset1:32
	ds_read2_b32 v[152:153], v250 offset0:29 offset1:30
	ds_read2_b32 v[154:155], v250 offset0:15 offset1:16
	ds_read2_b32 v[156:157], v250 offset0:13 offset1:14
	s_setprio 1
	s_waitcnt lgkmcnt(11)
	v_mfma_f32_16x16x32_bf16 v[98:101], v[116:119], v[0:3], 0
	v_mfma_f32_16x16x32_bf16 v[36:39], v[116:119], v[8:11], 0
	s_waitcnt lgkmcnt(10)
	v_mfma_f32_16x16x32_bf16 v[106:109], v[168:171], v[8:11], 0
	v_mfma_f32_16x16x32_bf16 v[102:105], v[168:171], v[0:3], 0
	s_waitcnt lgkmcnt(9)
	v_mfma_f32_16x16x32_bf16 v[40:43], v[172:175], v[12:15], v[36:39]
	s_waitcnt lgkmcnt(8)
	v_mfma_f32_16x16x32_bf16 v[36:39], v[192:195], v[12:15], v[106:109]
	v_mfma_f32_16x16x32_bf16 v[98:101], v[172:175], v[4:7], v[98:101]
	v_mfma_f32_16x16x32_bf16 v[102:105], v[192:195], v[4:7], v[102:105]
	s_setprio 0
	s_waitcnt lgkmcnt(7)
	s_nop 4
	v_fmamk_f32 v91, v98, 0x3e38aa3b, v139
	v_fmamk_f32 v84, v99, 0x3e38aa3b, v138
	s_waitcnt lgkmcnt(6)
	v_fmamk_f32 v85, v100, 0x3e38aa3b, v141
	v_fmamk_f32 v46, v101, 0x3e38aa3b, v140
	s_waitcnt lgkmcnt(5)
	v_fmamk_f32 v45, v102, 0x3e38aa3b, v143
	v_fmamk_f32 v44, v103, 0x3e38aa3b, v142
	v_max3_f32 v47, v91, v84, v85
	s_waitcnt lgkmcnt(4)
	v_fmamk_f32 v92, v104, 0x3e38aa3b, v149
	v_fmamk_f32 v86, v105, 0x3e38aa3b, v148
	v_max3_f32 v87, v46, v45, v44
	v_max_f32_e32 v88, v92, v86
	v_max3_f32 v47, v88, v47, v87
	v_cndmask_b32_e64 v47, v47, v225, s[36:37]
	v_add_f32_e32 v87, 0x41000000, v188
	v_cmp_gt_f32_e32 vcc, v47, v87
	s_cbranch_vccz .LBB0_444
	ds_bpermute_b32 v87, v233, v47
	v_max_f32_e32 v47, v47, v47
	v_mov_b32_e32 v89, v189
	s_waitcnt lgkmcnt(0)
	v_max_f32_e32 v87, v87, v87
	v_max_f32_e32 v47, v47, v87
	ds_bpermute_b32 v87, v234, v47
	s_waitcnt lgkmcnt(0)
	v_max3_f32 v88, v188, v47, v87
	v_sub_f32_e32 v47, v188, v88
	v_exp_f32_e32 v98, v47
	v_mov_b64_e32 v[188:189], v[88:89]
	v_mul_f32_e32 v190, v190, v98
	v_pk_mul_f32 v[74:75], v[74:75], v[98:99] op_sel_hi:[1,0]
	v_pk_mul_f32 v[72:73], v[72:73], v[98:99] op_sel_hi:[1,0]
	v_pk_mul_f32 v[26:27], v[26:27], v[98:99] op_sel_hi:[1,0]
	v_pk_mul_f32 v[24:25], v[24:25], v[98:99] op_sel_hi:[1,0]
	v_pk_mul_f32 v[22:23], v[22:23], v[98:99] op_sel_hi:[1,0]
	v_pk_mul_f32 v[20:21], v[20:21], v[98:99] op_sel_hi:[1,0]
	v_pk_mul_f32 v[18:19], v[18:19], v[98:99] op_sel_hi:[1,0]
	v_pk_mul_f32 v[16:17], v[16:17], v[98:99] op_sel_hi:[1,0]
	s_branch .LBB0_445

; template <int MODE>
; __device__ __forceinline__ void nsa_compute(int cur, int buf, int t, int hl, u64 mymask, const bf16x8 (&Qf)[2][2], f32x4 (&O)[4][2], float (&m)[2], float (&l)[2],
;                                             const float (&inv)[2], float* impw, char* lds) {
;     ...
;     for (int ks = 0; ks < 2; ++ks)
; #pragma unroll
;       for (int kk = 0; kk < 2; ++kk) kfr[ks][kk] = *(const bf16x8*)(kt + (32 * s2 + 16 * kk + fr) * 128 + (((ks * 4 + fq) ^ (fr & 7)) << 4));
;     __builtin_amdgcn_s_setprio(1);
; #pragma unroll
;     for (int ks = 0; ks < 2; ++ks)
; #pragma unroll
;       for (int kk = 0; kk < 2; ++kk)
; #pragma unroll
;         for (int r = 0; r < 2; ++r) S[kk][r] = mfma16(kfr[ks][kk], Qf[r][ks], S[kk][r]);
;     __builtin_amdgcn_s_setprio(0);
;     bf16x8 Pf[2];
;     float g1s[2] = {0.f, 0.f}, p3s[2] = {0.f, 0.f};
; #pragma unroll
;     for (int r = 0; r < 2; ++r) {
;       float sv[2][4];
; #pragma unroll
;       for (int kk = 0; kk < 2; ++kk)
; #pragma unroll
;         for (int e = 0; e < 4; ++e) {
;           const int off = 32 * s2 + 16 * kk + e;
;           int idx;
;           if (MODE <= 1) { idx = base - 16 * off; idx = idx > 0 ? idx : 0; } else idx = base - off;
;     ...
;           for (int e = 0; e < 4; ++e) { pv[kk][e] = __builtin_amdgcn_exp2f(sv[kk][e] - me); ps += pv[kk][e]; }
;         l[r] += ps;
;       }
;       if (MODE != 0) {
;         const unsigned w0 = pk2(pv[0][0], pv[0][1]), w1 = pk2(pv[0][2], pv[0][3]), w2 = pk2(pv[1][0], pv[1][1]), w3 = pk2(pv[1][2], pv[1][3]);
;         u32x4 pw; pw.x = w0; pw.y = w1; pw.z = w2; pw.w = w3;
;         Pf[r] = __builtin_bit_cast(bf16x8, pw);
;       }
;     }
;     if (MODE != 0) {
;       bf16x8 vfr[4];
; #pragma unroll
;       for (int df = 0; df < 4; ++df) {
;         const bf16x4 va = *(const bf16x4*)(vt + (df * 16 + fr) * 68 + 32 * s2 + 4 * fq);
;         const bf16x4 vb = *(const bf16x4*)(vt + (df * 16 + fr) * 68 + 32 * s2 + 16 + 4 * fq);
;         bf16x8 vf; vf[0] = va[0]; vf[1] = va[1]; vf[2] = va[2]; vf[3] = va[3]; vf[4] = vb[0]; vf[5] = vb[1]; vf[6] = vb[2]; vf[7] = vb[3];
;         vfr[df] = vf;
;       }
;       __builtin_amdgcn_s_setprio(1);
; #pragma unroll
;       for (int df = 0; df < 4; ++df)
; #pragma unroll
;         for (int r = 0; r < 2; ++r) O[df][r] = mfma16(vfr[df], Pf[r], O[df][r]);
;       __builtin_amdgcn_s_setprio(0);
.LBB0_459:
	v_cndmask_b32_e64 v30, v30, v228, s[36:37]
	v_sub_f32_e32 v31, v47, v30
	v_exp_f32_e32 v31, v31
	v_sub_f32_e32 v46, v46, v30
	v_exp_f32_e32 v46, v46
	v_sub_f32_e32 v113, v113, v30
	v_exp_f32_e32 v113, v113
	v_sub_f32_e32 v112, v112, v30
	v_exp_f32_e32 v112, v112
	v_sub_f32_e32 v45, v45, v30
	v_add_f32_e32 v47, 0, v31
	v_exp_f32_e32 v45, v45
	v_sub_f32_e32 v44, v44, v30
	v_add_f32_e32 v47, v46, v47
	v_exp_f32_e32 v44, v44
	v_sub_f32_e32 v29, v29, v30
	v_add_f32_e32 v47, v113, v47
	v_exp_f32_e32 v29, v29
	v_sub_f32_e32 v28, v28, v30
	v_add_f32_e32 v47, v112, v47
	v_exp_f32_e32 v28, v28
	v_add_f32_e32 v47, v45, v47
	v_add_f32_e32 v47, v44, v47
	v_add_f32_e32 v47, v29, v47
	s_lshl_b32 s16, s74, 9
	v_add_f32_e32 v30, v28, v47
	v_cvt_pk_bf16_f32 v135, v29, v28
	v_mul_u32_u24_e32 v28, 0x44, v117
	s_add_i32 s73, s72, s16
	v_lshlrev_b32_e32 v28, 1, v28
	v_lshlrev_b32_e32 v29, 1, v118
	v_add3_u32 v28, s73, v28, v29
	v_cvt_pk_bf16_f32 v129, v121, v123
	v_cvt_pk_bf16_f32 v130, v124, v125
	v_add_u32_e32 v123, 0x4000, v28
	v_add_u32_e32 v124, 0x4800, v28
	v_cvt_pk_bf16_f32 v128, v119, v120
	v_cvt_pk_bf16_f32 v131, v126, v127
	v_cvt_pk_bf16_f32 v132, v31, v46
	v_cvt_pk_bf16_f32 v134, v45, v44
	ds_read2_b64 v[44:47], v123 offset1:4
	ds_read2_b64 v[118:121], v124 offset0:16 offset1:20
	v_add_u32_e32 v125, 0x5000, v28
	v_add_u32_e32 v126, 0x5800, v28
	ds_read2_b64 v[136:139], v125 offset0:32 offset1:36
	ds_read2_b64 v[140:143], v126 offset0:48 offset1:52
	v_add_f32_e32 v147, v147, v30
	v_cvt_pk_bf16_f32 v133, v113, v112
	v_add_u32_e32 v127, v115, v114
	v_add_u32_e32 v148, v116, v114
	ds_read_b128 v[198:201], v127 offset:4096
	ds_read_b128 v[202:205], v127 offset:6144
	ds_read_b128 v[206:209], v148 offset:4096
	ds_read_b128 v[236:239], v148 offset:6144
	s_setprio 1
	s_waitcnt lgkmcnt(7)
	v_mfma_f32_16x16x32_bf16 v[28:31], v[44:47], v[128:131], v[24:27]
	v_mfma_f32_16x16x32_bf16 v[44:47], v[44:47], v[132:135], v[36:39]
	s_waitcnt lgkmcnt(6)
	v_mfma_f32_16x16x32_bf16 v[24:27], v[118:121], v[128:131], v[16:19]
	v_mfma_f32_16x16x32_bf16 v[40:43], v[118:121], v[132:135], v[40:43]
	s_waitcnt lgkmcnt(5)
	v_mfma_f32_16x16x32_bf16 v[20:23], v[136:139], v[128:131], v[20:23]
	v_mfma_f32_16x16x32_bf16 v[36:39], v[136:139], v[132:135], v[104:107]
	s_waitcnt lgkmcnt(4)
	v_mfma_f32_16x16x32_bf16 v[16:19], v[140:143], v[128:131], v[32:35]
	v_mfma_f32_16x16x32_bf16 v[32:35], v[140:143], v[132:135], v[108:111]
	s_setprio 0
	s_nop 1
	v_add_u32_e32 v108, v115, v114
	v_add_u32_e32 v116, v116, v114
	v_add_u32_e32 v251, 0x8400, v122
	v_add_u32_e32 v250, 0xc500, v122
	ds_read2_b32 v[152:153], v251 offset0:31 offset1:32
	ds_read2_b32 v[154:155], v251 offset0:29 offset1:30
	ds_read2_b32 v[156:157], v251 offset0:15 offset1:16
	ds_read2_b32 v[168:169], v251 offset0:13 offset1:14
	ds_read2_b32 v[170:171], v250 offset0:31 offset1:32
	ds_read2_b32 v[172:173], v250 offset0:29 offset1:30
	ds_read2_b32 v[174:175], v250 offset0:15 offset1:16
	ds_read2_b32 v[192:193], v250 offset0:13 offset1:14
	s_setprio 1
	s_waitcnt lgkmcnt(11)
	v_mfma_f32_16x16x32_bf16 v[128:131], v[198:201], v[0:3], 0
	v_mfma_f32_16x16x32_bf16 v[104:107], v[198:201], v[8:11], 0
	s_waitcnt lgkmcnt(10)
	v_mfma_f32_16x16x32_bf16 v[136:139], v[202:205], v[8:11], 0
	v_mfma_f32_16x16x32_bf16 v[132:135], v[202:205], v[0:3], 0
	s_waitcnt lgkmcnt(9)
	v_mfma_f32_16x16x32_bf16 v[128:131], v[206:209], v[4:7], v[128:131]
	v_mfma_f32_16x16x32_bf16 v[108:111], v[206:209], v[12:15], v[104:107]
	s_waitcnt lgkmcnt(8)
	v_mfma_f32_16x16x32_bf16 v[104:107], v[236:239], v[12:15], v[136:139]
	v_mfma_f32_16x16x32_bf16 v[132:135], v[236:239], v[4:7], v[132:135]
	s_setprio 0
	s_waitcnt lgkmcnt(7)
	s_nop 1
	v_fmamk_f32 v127, v128, 0x3e38aa3b, v153
	v_fmamk_f32 v116, v129, 0x3e38aa3b, v152
	s_waitcnt lgkmcnt(6)
	v_fmamk_f32 v117, v130, 0x3e38aa3b, v155
	v_fmamk_f32 v114, v131, 0x3e38aa3b, v154
	s_waitcnt lgkmcnt(5)
	v_fmamk_f32 v113, v132, 0x3e38aa3b, v157
	v_fmamk_f32 v112, v133, 0x3e38aa3b, v156
	v_max3_f32 v115, v127, v116, v117
	s_waitcnt lgkmcnt(4)
	v_fmamk_f32 v128, v134, 0x3e38aa3b, v169
	v_fmamk_f32 v118, v135, 0x3e38aa3b, v168
	v_max3_f32 v119, v114, v113, v112
	v_max_f32_e32 v120, v128, v118
	v_max3_f32 v115, v120, v115, v119
	v_cndmask_b32_e64 v115, v115, v225, s[36:37]
	v_add_f32_e32 v119, 0x41000000, v188
	v_cmp_gt_f32_e32 vcc, v115, v119
	s_cbranch_vccz .LBB0_461
	ds_bpermute_b32 v119, v233, v115
	v_max_f32_e32 v115, v115, v115
	v_mov_b32_e32 v121, v189
	s_waitcnt lgkmcnt(0)
	v_max_f32_e32 v119, v119, v119
	v_max_f32_e32 v115, v115, v119
	ds_bpermute_b32 v119, v234, v115
	s_waitcnt lgkmcnt(0)
	v_max3_f32 v120, v188, v115, v119
	v_sub_f32_e32 v115, v188, v120
	v_exp_f32_e32 v130, v115
	v_mov_b64_e32 v[188:189], v[120:121]
	v_mul_f32_e32 v146, v146, v130
	v_pk_mul_f32 v[30:31], v[30:31], v[130:131] op_sel_hi:[1,0]
	v_pk_mul_f32 v[28:29], v[28:29], v[130:131] op_sel_hi:[1,0]
	v_pk_mul_f32 v[26:27], v[26:27], v[130:131] op_sel_hi:[1,0]
	v_pk_mul_f32 v[24:25], v[24:25], v[130:131] op_sel_hi:[1,0]
	v_pk_mul_f32 v[22:23], v[22:23], v[130:131] op_sel_hi:[1,0]
	v_pk_mul_f32 v[20:21], v[20:21], v[130:131] op_sel_hi:[1,0]
	v_pk_mul_f32 v[18:19], v[18:19], v[130:131] op_sel_hi:[1,0]
	v_pk_mul_f32 v[16:17], v[16:17], v[130:131] op_sel_hi:[1,0]
	s_branch .LBB0_462

; template <int MODE>
; __device__ __forceinline__ void nsa_compute(int cur, int buf, int t, int hl, u64 mymask, const bf16x8 (&Qf)[2][2], f32x4 (&O)[4][2], float (&m)[2], float (&l)[2],
;                                             const float (&inv)[2], float* impw, char* lds) {
;     ...
;     for (int ks = 0; ks < 2; ++ks)
; #pragma unroll
;       for (int kk = 0; kk < 2; ++kk) kfr[ks][kk] = *(const bf16x8*)(kt + (32 * s2 + 16 * kk + fr) * 128 + (((ks * 4 + fq) ^ (fr & 7)) << 4));
;     __builtin_amdgcn_s_setprio(1);
; #pragma unroll
;     for (int ks = 0; ks < 2; ++ks)
; #pragma unroll
;       for (int kk = 0; kk < 2; ++kk)
; #pragma unroll
;         for (int r = 0; r < 2; ++r) S[kk][r] = mfma16(kfr[ks][kk], Qf[r][ks], S[kk][r]);
;     __builtin_amdgcn_s_setprio(0);
;     bf16x8 Pf[2];
;     float g1s[2] = {0.f, 0.f}, p3s[2] = {0.f, 0.f};
; #pragma unroll
;     for (int r = 0; r < 2; ++r) {
;       float sv[2][4];
; #pragma unroll
;       for (int kk = 0; kk < 2; ++kk)
; #pragma unroll
;         for (int e = 0; e < 4; ++e) {
;           const int off = 32 * s2 + 16 * kk + e;
;           int idx;
;           if (MODE <= 1) { idx = base - 16 * off; idx = idx > 0 ? idx : 0; } else idx = base - off;
;     ...
;           for (int e = 0; e < 4; ++e) { pv[kk][e] = __builtin_amdgcn_exp2f(sv[kk][e] - me); ps += pv[kk][e]; }
;         l[r] += ps;
;       }
;       if (MODE != 0) {
;         const unsigned w0 = pk2(pv[0][0], pv[0][1]), w1 = pk2(pv[0][2], pv[0][3]), w2 = pk2(pv[1][0], pv[1][1]), w3 = pk2(pv[1][2], pv[1][3]);
;         u32x4 pw; pw.x = w0; pw.y = w1; pw.z = w2; pw.w = w3;
;         Pf[r] = __builtin_bit_cast(bf16x8, pw);
;       }
;     }
;     if (MODE != 0) {
;       bf16x8 vfr[4];
; #pragma unroll
;       for (int df = 0; df < 4; ++df) {
;         const bf16x4 va = *(const bf16x4*)(vt + (df * 16 + fr) * 68 + 32 * s2 + 4 * fq);
;         const bf16x4 vb = *(const bf16x4*)(vt + (df * 16 + fr) * 68 + 32 * s2 + 16 + 4 * fq);
;         bf16x8 vf; vf[0] = va[0]; vf[1] = va[1]; vf[2] = va[2]; vf[3] = va[3]; vf[4] = vb[0]; vf[5] = vb[1]; vf[6] = vb[2]; vf[7] = vb[3];
;         vfr[df] = vf;
;       }
;       __builtin_amdgcn_s_setprio(1);
; #pragma unroll
;       for (int df = 0; df < 4; ++df)
; #pragma unroll
;         for (int r = 0; r < 2; ++r) O[df][r] = mfma16(vfr[df], Pf[r], O[df][r]);
;       __builtin_amdgcn_s_setprio(0);
.LBB0_476:
	v_cvt_pk_bf16_f32 v152, v152, v153
	v_cvt_pk_bf16_f32 v153, v154, v155
	v_cvt_pk_bf16_f32 v154, v156, v157
	v_cndmask_b32_e64 v156, v161, v228, s[36:37]
	v_sub_f32_e32 v139, v139, v156
	v_exp_f32_e32 v139, v139
	v_sub_f32_e32 v138, v138, v156
	v_exp_f32_e32 v138, v138
	v_sub_f32_e32 v141, v141, v156
	v_exp_f32_e32 v141, v141
	v_sub_f32_e32 v140, v140, v156
	v_exp_f32_e32 v140, v140
	v_sub_f32_e32 v137, v137, v156
	v_cvt_pk_bf16_f32 v155, v159, v160
	v_add_f32_e32 v157, 0, v139
	v_exp_f32_e32 v159, v137
	v_add_f32_e32 v157, v138, v157
	v_add_f32_e32 v157, v141, v157
	v_add_f32_e32 v157, v140, v157
	v_sub_f32_e32 v136, v136, v156
	v_add_f32_e32 v137, v159, v157
	v_exp_f32_e32 v157, v136
	s_nop 0
	v_add_f32_e32 v136, v157, v137
	v_sub_f32_e32 v137, v143, v156
	v_exp_f32_e32 v143, v137
	v_sub_f32_e32 v137, v142, v156
	v_exp_f32_e32 v142, v137
	v_cvt_pk_bf16_f32 v137, v141, v140
	v_mul_u32_u24_e32 v140, 0x44, v150
	v_add_f32_e32 v136, v143, v136
	v_lshlrev_b32_e32 v140, 1, v140
	v_lshlrev_b32_e32 v141, 1, v151
	v_add_f32_e32 v136, v142, v136
	v_add3_u32 v150, s71, v140, v141
	v_add_f32_e32 v191, v191, v136
	v_cvt_pk_bf16_f32 v136, v139, v138
	v_cvt_pk_bf16_f32 v138, v159, v157
	v_add_u32_e32 v159, 0x4000, v150
	v_add_u32_e32 v160, 0x4800, v150
	v_cvt_pk_bf16_f32 v139, v143, v142
	ds_read2_b64 v[140:143], v159 offset1:4
	ds_read2_b64 v[164:167], v160 offset0:16 offset1:20
	v_add_u32_e32 v161, 0x5000, v150
	v_add_u32_e32 v162, 0x5800, v150
	ds_read2_b64 v[168:171], v161 offset0:32 offset1:36
	ds_read2_b64 v[172:175], v162 offset0:48 offset1:52
	ds_read_b128 v[236:239], v148 offset:4096
	ds_read_b128 v[240:243], v148 offset:6144
	ds_read_b128 v[244:247], v149 offset:4096
	s_setprio 1
	s_waitcnt lgkmcnt(6)
	v_mfma_f32_16x16x32_bf16 v[16:19], v[140:143], v[152:155], v[16:19]
	v_mfma_f32_16x16x32_bf16 v[20:23], v[140:143], v[136:139], v[20:23]
	s_waitcnt lgkmcnt(5)
	v_mfma_f32_16x16x32_bf16 v[24:27], v[164:167], v[152:155], v[24:27]
	v_mfma_f32_16x16x32_bf16 v[28:31], v[164:167], v[136:139], v[28:31]
	s_waitcnt lgkmcnt(4)
	v_mfma_f32_16x16x32_bf16 v[32:35], v[168:171], v[152:155], v[32:35]
	v_mfma_f32_16x16x32_bf16 v[36:39], v[168:171], v[136:139], v[36:39]
	s_waitcnt lgkmcnt(3)
	v_mfma_f32_16x16x32_bf16 v[40:43], v[172:175], v[152:155], v[40:43]
	v_mfma_f32_16x16x32_bf16 v[44:47], v[172:175], v[136:139], v[44:47]
	s_setprio 0
	ds_read_b128 v[154:157], v149 offset:6144
	v_add_u32_e32 v251, 0x8400, v158
	v_add_u32_e32 v250, 0xc500, v158
	ds_read2_b32 v[192:193], v251 offset0:31 offset1:32
	ds_read2_b32 v[194:195], v251 offset0:29 offset1:30
	ds_read2_b32 v[198:199], v251 offset0:15 offset1:16
	ds_read2_b32 v[200:201], v251 offset0:13 offset1:14
	ds_read2_b32 v[202:203], v250 offset0:31 offset1:32
	ds_read2_b32 v[204:205], v250 offset0:29 offset1:30
	ds_read2_b32 v[206:207], v250 offset0:15 offset1:16
	ds_read2_b32 v[208:209], v250 offset0:13 offset1:14
	s_setprio 1
	s_waitcnt lgkmcnt(11)
	v_mfma_f32_16x16x32_bf16 v[164:167], v[236:239], v[0:3], 0
	v_mfma_f32_16x16x32_bf16 v[136:139], v[236:239], v[8:11], 0
	s_waitcnt lgkmcnt(10)
	v_mfma_f32_16x16x32_bf16 v[172:175], v[240:243], v[8:11], 0
	v_mfma_f32_16x16x32_bf16 v[168:171], v[240:243], v[0:3], 0
	s_waitcnt lgkmcnt(9)
	v_mfma_f32_16x16x32_bf16 v[164:167], v[244:247], v[4:7], v[164:167]
	v_mfma_f32_16x16x32_bf16 v[140:143], v[244:247], v[12:15], v[136:139]
	s_waitcnt lgkmcnt(8)
	v_mfma_f32_16x16x32_bf16 v[136:139], v[154:157], v[12:15], v[172:175]
	v_mfma_f32_16x16x32_bf16 v[168:171], v[154:157], v[4:7], v[168:171]
	s_setprio 0
	s_waitcnt lgkmcnt(7)
	s_nop 1
	v_fmamk_f32 v163, v164, 0x3e38aa3b, v193
	v_fmamk_f32 v152, v165, 0x3e38aa3b, v192
	s_waitcnt lgkmcnt(6)
	v_fmamk_f32 v153, v166, 0x3e38aa3b, v195
	v_fmamk_f32 v150, v167, 0x3e38aa3b, v194
	s_waitcnt lgkmcnt(5)
	v_fmamk_f32 v149, v168, 0x3e38aa3b, v199
	v_fmamk_f32 v148, v169, 0x3e38aa3b, v198
	v_max3_f32 v151, v163, v152, v153
	s_waitcnt lgkmcnt(4)
	v_fmamk_f32 v164, v170, 0x3e38aa3b, v201
	v_fmamk_f32 v154, v171, 0x3e38aa3b, v200
	v_max3_f32 v155, v150, v149, v148
	v_max_f32_e32 v156, v164, v154
	v_max3_f32 v151, v156, v151, v155
	v_cndmask_b32_e64 v151, v151, v225, s[36:37]
	v_add_f32_e32 v155, 0x41000000, v188
	v_cmp_gt_f32_e32 vcc, v151, v155
	s_cbranch_vccz .LBB0_478
	ds_bpermute_b32 v155, v233, v151
	v_max_f32_e32 v151, v151, v151
	v_mov_b32_e32 v157, v189
	s_waitcnt lgkmcnt(0)
	v_max_f32_e32 v155, v155, v155
	v_max_f32_e32 v151, v151, v155
	ds_bpermute_b32 v155, v234, v151
	s_waitcnt lgkmcnt(0)
	v_max3_f32 v156, v188, v151, v155
	v_sub_f32_e32 v151, v188, v156
	v_exp_f32_e32 v166, v151
	v_mov_b64_e32 v[188:189], v[156:157]
	v_mul_f32_e32 v190, v190, v166
	v_pk_mul_f32 v[18:19], v[18:19], v[166:167] op_sel_hi:[1,0]
	v_pk_mul_f32 v[16:17], v[16:17], v[166:167] op_sel_hi:[1,0]
	v_pk_mul_f32 v[26:27], v[26:27], v[166:167] op_sel_hi:[1,0]
	v_pk_mul_f32 v[24:25], v[24:25], v[166:167] op_sel_hi:[1,0]
	v_pk_mul_f32 v[34:35], v[34:35], v[166:167] op_sel_hi:[1,0]
	v_pk_mul_f32 v[32:33], v[32:33], v[166:167] op_sel_hi:[1,0]
	v_pk_mul_f32 v[42:43], v[42:43], v[166:167] op_sel_hi:[1,0]
	v_pk_mul_f32 v[40:41], v[40:41], v[166:167] op_sel_hi:[1,0]
	s_branch .LBB0_479
